# grid barriers 2..13 rewritten: fixed per-XCD leader, monotonic counters, compact thread-0 body
# speedup vs baseline: 1.0028x; 1.0028x over previous
.Lgs_done:
	s_or_b64 exec, exec, s[6:7]
	s_waitcnt lgkmcnt(0)
	s_and_saveexec_b64 s[6:7], s[38:39]
	s_cbranch_execz .LBB0_30
	s_mov_b64 s[8:9], exec
	v_mbcnt_lo_u32_b32 v0, s8, 0
	v_mbcnt_hi_u32_b32 v0, s9, v0
	v_cmp_eq_u32_e32 vcc, 0, v0
	s_and_b64 s[10:11], exec, vcc
	s_mov_b64 exec, s[10:11]
	s_cbranch_execz .LBB0_30
	s_lshl_b32 s3, s3, 8
	s_and_b32 s3, s3, 0xf00
	s_add_u32 s4, s4, s3
	s_addc_u32 s5, s5, 0
	s_bcnt1_i32_b64 s3, s[8:9]
	v_mov_b32_e32 v0, 0x7798000
	v_mov_b32_e32 v1, s3
	global_atomic_add v2, v0, v1, s[4:5] offset:1024 sc0
	s_waitcnt vmcnt(0)
	v_readfirstlane_b32 s101, v2

.Lxb0_123:
	s_or_b64 exec, exec, s[4:5]
	s_mov_b64 s[4:5], s[0:1]
	v_mov_b32_e32 v2, v170
	s_waitcnt lgkmcnt(0)
	s_barrier
	v_mov_b32_e32 v0, 0x22000
	ds_read_b32 v1, v0
	ds_read_b32 v2, v0 offset:4
	s_mov_b32 s98, 1
	s_waitcnt lgkmcnt(0)
	v_readfirstlane_b32 s99, v1
	v_readfirstlane_b32 s100, v2
	s_cmp_lg_u32 s2, 0
	s_cbranch_scc1 .Lgs_noreset
	s_and_saveexec_b64 s[6:7], s[38:39]
	s_load_dwordx2 s[8:9], s[88:89], 0x58
	v_mov_b32_e32 v0, 0
	v_mov_b32_e32 v1, -1
	s_waitcnt lgkmcnt(0)
	global_atomic_add v0, v1, s[8:9] offset:32
	s_or_b64 exec, exec, s[6:7]

.LBB0_71:
	s_mov_b64 s[6:7], s[0:1]
	s_getreg_b32 s3, hwreg(HW_REG_XCC_ID, 0, 4)
	s_waitcnt vmcnt(0)
	s_barrier
	s_and_saveexec_b64 s[4:5], s[38:39]
	s_cbranch_execz .LBB0_123
	s_and_b32 s20, s3, 15
	s_load_dwordx2 s[18:19], s[0:1], 0xe8
	s_add_i32 s98, s98, 1
	s_lshl_b32 s20, s20, 8
	v_mov_b32_e32 v0, 0
	v_mov_b32_e32 v1, 1
	s_waitcnt lgkmcnt(0)
	s_add_u32 s18, s18, 0x7798000
	s_addc_u32 s19, s19, 0
	s_add_u32 s24, s18, s20
	s_addc_u32 s25, s19, 0
	s_add_u32 s26, s24, 0x1400
	s_addc_u32 s27, s25, 0
	s_add_u32 s30, s24, 0x2400
	s_addc_u32 s31, s25, 0
	global_atomic_add v0, v1, s[26:27]
	s_cmp_lg_u32 s101, 0
	s_cbranch_scc1 .Lxbn0_fol
	s_mul_i32 s21, s98, s99
	s_mov_b32 s22, 0
.Lxbn0_p1:
	global_load_dword v2, v0, s[26:27] sc1
	s_waitcnt vmcnt(0)
	v_readfirstlane_b32 s23, v2
	s_cmp_ge_u32 s23, s21
	s_cbranch_scc1 .Lxbn0_p1_ok
	s_sleep 1
	s_add_i32 s22, s22, 1
	s_cmp_lt_u32 s22, 0x40000
	s_cbranch_scc1 .Lxbn0_p1
.Lxbn0_p1_ok:
	buffer_wbl2 sc1
	s_waitcnt vmcnt(0)
	s_add_u32 s28, s18, 0x3400
	s_addc_u32 s29, s19, 0
	global_atomic_add v0, v1, s[28:29]
	s_mul_i32 s21, s98, s100
	s_mov_b32 s22, 0
.Lxbn0_p2:
	global_load_dword v2, v0, s[28:29] sc1
	s_waitcnt vmcnt(0)
	v_readfirstlane_b32 s23, v2
	s_cmp_ge_u32 s23, s21
	s_cbranch_scc1 .Lxbn0_p2_ok
	s_sleep 1
	s_add_i32 s22, s22, 1
	s_cmp_lt_u32 s22, 0x40000
	s_cbranch_scc1 .Lxbn0_p2
.Lxbn0_p2_ok:
	buffer_inv sc1
	global_atomic_add v0, v1, s[30:31]
	s_waitcnt vmcnt(0)
	s_branch .Lxbn0_end
.Lxbn0_fol:
	s_mov_b32 s22, 0
.Lxbn0_p3:
	global_load_dword v2, v0, s[30:31] sc1
	s_waitcnt vmcnt(0)
	v_readfirstlane_b32 s23, v2
	s_cmp_ge_u32 s23, s98
	s_cbranch_scc1 .Lxbn0_p3_ok
	s_sleep 1
	s_add_i32 s22, s22, 1
	s_cmp_lt_u32 s22, 0x40000
	s_cbranch_scc1 .Lxbn0_p3

.Lxbn0_end:
.LBB0_123:
	s_or_b64 exec, exec, s[4:5]
	s_mov_b64 s[4:5], s[0:1]
	v_mov_b32_e32 v2, v170
	s_waitcnt lgkmcnt(0)
	s_barrier
	s_lshl_b32 s46, s2, 3
	v_ashrrev_i32_e32 v0, 6, v2
	v_add_u32_e32 v3, s46, v0
	s_movk_i32 s3, 0x3000
	s_lshl_b32 s44, s42, 3
	v_cmp_gt_i32_e32 vcc, s3, v3
	v_mbcnt_lo_u32_b32 v135, -1, 0
	s_and_saveexec_b64 s[10:11], vcc
	s_cbranch_execz .LBB0_134
	v_lshlrev_b32_e32 v1, 2, v2
	v_and_b32_e32 v4, 0xfc, v1
	v_mbcnt_hi_u32_b32 v1, -1, v135
	v_and_b32_e32 v6, 64, v1
	v_xor_b32_e32 v5, 32, v1
	v_add_u32_e32 v6, 64, v6
	v_cmp_lt_i32_e32 vcc, v5, v6
	s_load_dwordx2 s[6:7], s[4:5], 0xe8
	s_load_dwordx4 s[12:15], s[4:5], 0x0
	v_cndmask_b32_e32 v5, v1, v5, vcc
	v_lshlrev_b32_e32 v66, 2, v5
	v_xor_b32_e32 v5, 16, v1
	v_cmp_lt_i32_e32 vcc, v5, v6
	s_waitcnt lgkmcnt(0)
	s_add_u32 s18, s6, 0x780000
	s_addc_u32 s19, s7, 0
	v_cndmask_b32_e32 v5, v1, v5, vcc
	v_lshlrev_b32_e32 v67, 2, v5
	v_xor_b32_e32 v5, 8, v1
	v_cmp_lt_i32_e32 vcc, v5, v6
	s_ashr_i32 s47, s46, 31
	v_add_u32_e32 v56, s44, v3
	v_cndmask_b32_e32 v5, v1, v5, vcc
	v_lshlrev_b32_e32 v68, 2, v5
	v_xor_b32_e32 v5, 4, v1
	v_cmp_lt_i32_e32 vcc, v5, v6
	v_ashrrev_i32_e32 v57, 31, v56
	v_mov_b32_e32 v49, 0
	v_cndmask_b32_e32 v5, v1, v5, vcc
	v_lshlrev_b32_e32 v69, 2, v5
	v_xor_b32_e32 v5, 2, v1
	v_cmp_lt_i32_e32 vcc, v5, v6
	v_lshlrev_b32_e32 v48, 1, v4
	s_mov_b32 s17, 0
	v_cndmask_b32_e32 v5, v1, v5, vcc
	v_lshlrev_b32_e32 v70, 2, v5
	v_xor_b32_e32 v5, 1, v1
	v_cmp_lt_i32_e32 vcc, v5, v6
	v_lshl_add_u64 v[6:7], s[6:7], 0, v[48:49]
	s_mov_b64 s[4:5], 0x2ebc000
	v_cndmask_b32_e32 v1, v1, v5, vcc
	v_lshlrev_b32_e32 v71, 2, v1
	v_ashrrev_i32_e32 v1, 31, v0
	v_lshl_add_u64 v[52:53], v[0:1], 0, s[46:47]
	v_and_b32_e32 v0, 63, v2
	v_lshlrev_b32_e32 v54, 3, v0
	v_lshlrev_b64 v[0:1], 11, v[56:57]
	s_mul_i32 s20, s42, 24
	v_lshl_add_u64 v[58:59], s[6:7], 0, v[0:1]
	v_lshlrev_b64 v[0:1], 11, v[52:53]
	v_lshl_add_u64 v[50:51], v[6:7], 0, s[4:5]
	s_mov_b32 s45, s17
	s_ashr_i32 s21, s20, 31
	v_lshl_add_u64 v[0:1], s[6:7], 0, v[0:1]
	s_mov_b64 s[4:5], 0x2ebc400
	s_lshl_b32 s16, s42, 4
	v_mov_b32_e32 v55, v49
	s_lshl_b64 s[22:23], s[20:21], 11
	v_lshl_add_u64 v[60:61], v[0:1], 0, s[4:5]
	s_mov_b64 s[24:25], 0
	s_movk_i32 s40, 0x1000
	v_mov_b32_e32 v72, s15
	v_mov_b32_e32 v73, s13
	v_mov_b32_e32 v74, s14
	v_mov_b32_e32 v75, s12
	v_lshlrev_b32_e32 v48, 2, v4
	v_mov_b32_e32 v76, 0x358637bd
	s_mov_b32 s41, 0x800000
	s_mov_b64 s[26:27], 0x1000
	s_movk_i32 s47, 0xfff
	s_mov_b32 s52, 0x2ebc000
	s_movk_i32 s53, 0x2fff
	s_mov_b64 s[28:29], 0
	s_mov_b64 s[30:31], s[44:45]
	s_mov_b64 s[34:35], 0
	s_branch .LBB0_126

.LBB0_134:
	s_or_b64 exec, exec, s[10:11]
	s_mov_b64 s[6:7], s[0:1]
	s_getreg_b32 s3, hwreg(HW_REG_XCC_ID, 0, 4)
	s_waitcnt vmcnt(0)
	s_waitcnt lgkmcnt(0)
	s_barrier
	s_and_saveexec_b64 s[4:5], s[38:39]
	s_cbranch_execz .LBB0_186
	s_and_b32 s20, s3, 15
	s_load_dwordx2 s[18:19], s[0:1], 0xe8
	s_add_i32 s98, s98, 1
	s_lshl_b32 s20, s20, 8
	v_mov_b32_e32 v0, 0
	v_mov_b32_e32 v1, 1
	s_waitcnt lgkmcnt(0)
	s_add_u32 s18, s18, 0x7798000
	s_addc_u32 s19, s19, 0
	s_add_u32 s24, s18, s20
	s_addc_u32 s25, s19, 0
	s_add_u32 s26, s24, 0x1400
	s_addc_u32 s27, s25, 0
	s_add_u32 s30, s24, 0x2400
	s_addc_u32 s31, s25, 0
	global_atomic_add v0, v1, s[26:27]
	s_cmp_lg_u32 s101, 0
	s_cbranch_scc1 .Lxbn1_fol
	s_mul_i32 s21, s98, s99
	s_mov_b32 s22, 0

.Lxbn1_end:
.LBB0_186:
	s_or_b64 exec, exec, s[4:5]
	s_mov_b64 s[16:17], s[0:1]
	s_waitcnt lgkmcnt(0)
	s_barrier
	s_load_dwordx2 s[18:19], s[16:17], 0xe8
	v_mov_b32_e32 v14, v170
	s_cmpk_lt_i32 s2, 0x180
	s_cselect_b64 s[4:5], -1, 0
	s_cmpk_gt_i32 s2, 0x17f
	v_readfirstlane_b32 s45, v14
	s_cbranch_scc1 .LBB0_188
	s_ashr_i32 s3, s2, 31
	s_lshr_b32 s3, s3, 29
	s_add_i32 s3, s2, s3
	s_ashr_i32 s6, s3, 3
	s_and_b32 s3, s3, -8
	s_sub_i32 s3, s2, s3
	s_lshr_b32 s7, s3, 31
	s_or_b32 s7, s7, 48
	s_mul_i32 s3, s7, s3
	s_add_i32 s3, s3, s6
	s_ashr_i32 s6, s3, 31
	s_lshr_b32 s6, s6, 26
	s_add_i32 s6, s3, s6
	s_ashr_i32 s6, s6, 6
	s_lshl_b32 s8, s6, 3
	s_sub_i32 s7, 48, s8
	s_lshl_b32 s6, s6, 6
	s_min_u32 s9, s7, 8
	s_sub_i32 s3, s3, s6
	s_sext_i32_i8 s6, s3
	v_cvt_f32_ubyte0_e32 v1, s9
	v_cvt_f32_i32_e32 v0, s6
	v_rcp_iflag_f32_e32 v2, v1
	s_ashr_i32 s6, s6, 30
	s_or_b32 s10, s6, 1
	v_mul_f32_e32 v2, v0, v2
	v_trunc_f32_e32 v2, v2
	v_fma_f32 v0, -v2, v1, v0
	v_cvt_i32_f32_e32 v2, v2
	v_cmp_ge_f32_e64 s[6:7], |v0|, v1
	s_and_b64 s[6:7], s[6:7], exec
	s_cselect_b32 s6, s10, 0
	v_readfirstlane_b32 s7, v2
	s_add_i32 s6, s7, s6
	s_sext_i32_i8 s12, s6
	s_mul_i32 s6, s6, s9
	s_sub_i32 s3, s3, s6
	s_sext_i32_i8 s3, s3
	s_add_i32 s10, s8, s3

.LBB0_925:
	s_mov_b64 s[6:7], s[0:1]
	s_getreg_b32 s8, hwreg(HW_REG_XCC_ID, 0, 4)
	s_waitcnt vmcnt(0)
	s_waitcnt vmcnt(0) lgkmcnt(0)
	s_barrier
	s_and_saveexec_b64 s[4:5], s[38:39]
	s_cbranch_execz .LBB0_977
	s_and_b32 s20, s8, 15
	s_load_dwordx2 s[18:19], s[0:1], 0xe8
	s_add_i32 s98, s98, 1
	s_lshl_b32 s20, s20, 8
	v_mov_b32_e32 v0, 0
	v_mov_b32_e32 v1, 1
	s_waitcnt lgkmcnt(0)
	s_add_u32 s18, s18, 0x7798000
	s_addc_u32 s19, s19, 0
	s_add_u32 s24, s18, s20
	s_addc_u32 s25, s19, 0
	s_add_u32 s26, s24, 0x1400
	s_addc_u32 s27, s25, 0
	s_add_u32 s30, s24, 0x2400
	s_addc_u32 s31, s25, 0
	global_atomic_add v0, v1, s[26:27]
	s_cmp_lg_u32 s101, 0
	s_cbranch_scc1 .Lxbn2_fol
	s_mul_i32 s21, s98, s99
	s_mov_b32 s22, 0

.Lxbn2_end:
.LBB0_977:
	s_or_b64 exec, exec, s[4:5]
	s_mov_b64 s[20:21], s[0:1]
	v_mov_b32_e32 v133, v170
	s_waitcnt lgkmcnt(0)
	s_barrier
	s_load_dwordx2 s[4:5], s[20:21], 0x60
	v_and_b32_e32 v150, 63, v133
	v_lshlrev_b32_e32 v0, 2, v150
	s_waitcnt lgkmcnt(0)
	global_load_dword v1, v0, s[4:5]
	global_load_dword v2, v0, s[4:5] offset:256
	global_load_dword v3, v0, s[4:5] offset:512
	global_load_dword v4, v0, s[4:5] offset:768
	v_mbcnt_hi_u32_b32 v0, -1, v135
	v_and_b32_e32 v6, 64, v0
	v_xor_b32_e32 v5, 32, v0
	v_add_u32_e32 v6, 64, v6
	v_cmp_lt_i32_e32 vcc, v5, v6
	v_xor_b32_e32 v7, 16, v0
	v_xor_b32_e32 v8, 8, v0
	v_cndmask_b32_e32 v5, v0, v5, vcc
	v_lshlrev_b32_e32 v171, 2, v5
	v_cmp_lt_i32_e32 vcc, v7, v6
	v_xor_b32_e32 v9, 4, v0
	v_xor_b32_e32 v10, 2, v0
	v_cndmask_b32_e32 v7, v0, v7, vcc
	v_lshlrev_b32_e32 v172, 2, v7
	v_cmp_lt_i32_e32 vcc, v8, v6
	v_xor_b32_e32 v11, 1, v0
	s_mov_b32 s4, 0x3fb8aa3b
	s_mov_b32 s5, 0xc2ce8ed0
	s_mov_b32 s6, 0x42b17218
	s_waitcnt vmcnt(2)
	v_mul_f32_e32 v5, v1, v2
	ds_bpermute_b32 v5, v171, v5
	s_waitcnt vmcnt(0)
	v_mul_f32_e32 v12, v3, v4
	ds_bpermute_b32 v12, v171, v12
	s_waitcnt lgkmcnt(1)
	v_fmac_f32_e32 v5, v1, v2
	ds_bpermute_b32 v1, v172, v5
	s_waitcnt lgkmcnt(1)
	v_fmac_f32_e32 v12, v3, v4
	ds_bpermute_b32 v2, v172, v12
	v_cndmask_b32_e32 v3, v0, v8, vcc
	v_lshlrev_b32_e32 v173, 2, v3
	s_waitcnt lgkmcnt(1)
	v_add_f32_e32 v1, v5, v1
	ds_bpermute_b32 v3, v173, v1
	s_waitcnt lgkmcnt(1)
	v_add_f32_e32 v2, v12, v2
	ds_bpermute_b32 v4, v173, v2
	v_cmp_lt_i32_e32 vcc, v9, v6
	s_waitcnt lgkmcnt(1)
	v_add_f32_e32 v1, v1, v3
	v_cndmask_b32_e32 v5, v0, v9, vcc
	v_lshlrev_b32_e32 v174, 2, v5
	s_waitcnt lgkmcnt(0)
	v_add_f32_e32 v2, v2, v4
	ds_bpermute_b32 v3, v174, v1
	ds_bpermute_b32 v4, v174, v2
	v_cmp_lt_i32_e32 vcc, v10, v6
	s_waitcnt lgkmcnt(1)
	v_add_f32_e32 v1, v1, v3
	v_cndmask_b32_e32 v5, v0, v10, vcc
	v_lshlrev_b32_e32 v175, 2, v5
	s_waitcnt lgkmcnt(0)
	v_add_f32_e32 v2, v2, v4
	ds_bpermute_b32 v3, v175, v1
	ds_bpermute_b32 v4, v175, v2
	v_cmp_lt_i32_e32 vcc, v11, v6
	s_nop 1
	v_cndmask_b32_e32 v0, v0, v11, vcc
	v_lshlrev_b32_e32 v176, 2, v0
	s_waitcnt lgkmcnt(1)
	v_add_f32_e32 v0, v1, v3
	s_waitcnt lgkmcnt(0)
	v_add_f32_e32 v1, v2, v4
	ds_bpermute_b32 v2, v176, v0
	ds_bpermute_b32 v3, v176, v1
	v_mov_b32_e32 v4, 0x7f800000
	s_waitcnt lgkmcnt(1)
	v_add_f32_e32 v0, v0, v2
	s_waitcnt lgkmcnt(0)
	v_add_f32_e32 v1, v1, v3
	v_mul_f32_e32 v2, 0x3fb8aa3b, v0
	v_mul_f32_e32 v3, 0x3fb8aa3b, v1
	v_fma_f32 v5, v0, s4, -v2
	v_rndne_f32_e32 v6, v2
	v_fma_f32 v7, v1, s4, -v3
	v_rndne_f32_e32 v8, v3
	v_fmac_f32_e32 v5, 0x32a5705f, v0
	v_sub_f32_e32 v2, v2, v6
	v_fmac_f32_e32 v7, 0x32a5705f, v1
	v_sub_f32_e32 v3, v3, v8
	v_add_f32_e32 v2, v2, v5
	v_cvt_i32_f32_e32 v6, v6
	v_add_f32_e32 v3, v3, v7
	v_exp_f32_e32 v2, v2
	v_cvt_i32_f32_e32 v8, v8
	v_exp_f32_e32 v3, v3
	v_cmp_ngt_f32_e32 vcc, s5, v0
	v_ldexp_f32 v2, v2, v6
	s_and_b32 s4, s42, 7
	v_ldexp_f32 v3, v3, v8
	v_cndmask_b32_e32 v2, 0, v2, vcc
	v_cmp_ngt_f32_e32 vcc, s5, v1
	s_cmp_lg_u32 s4, 0
	s_mov_b32 s5, s2
	v_cndmask_b32_e32 v3, 0, v3, vcc
	v_cmp_nlt_f32_e32 vcc, s6, v0
	s_nop 1
	v_cndmask_b32_e32 v0, v4, v2, vcc
	v_cmp_nlt_f32_e32 vcc, s6, v1
	s_nop 1
	v_cndmask_b32_e32 v1, v4, v3, vcc
	v_sub_f32_e32 v0, v0, v1
	s_nop 0
	v_readfirstlane_b32 s4, v0
	s_cbranch_scc0 .LBB0_979
	v_mov_b32_e32 v0, 0x3e4ccccd
	s_cmpk_gt_i32 s5, 0xff
	v_add_f32_e32 v166, s4, v0
	s_cbranch_scc0 .LBB0_980
	s_branch .LBB0_1001

.LBB0_1031:
	s_mov_b64 s[6:7], s[0:1]
	s_getreg_b32 s8, hwreg(HW_REG_XCC_ID, 0, 4)
	s_waitcnt vmcnt(0)
	s_barrier
	s_and_saveexec_b64 s[4:5], s[38:39]
	s_cbranch_execz .LBB0_1083
	s_and_b32 s20, s8, 15
	s_load_dwordx2 s[18:19], s[0:1], 0xe8
	s_add_i32 s98, s98, 1
	s_lshl_b32 s20, s20, 8
	v_mov_b32_e32 v0, 0
	v_mov_b32_e32 v1, 1
	s_waitcnt lgkmcnt(0)
	s_add_u32 s18, s18, 0x7798000
	s_addc_u32 s19, s19, 0
	s_add_u32 s24, s18, s20
	s_addc_u32 s25, s19, 0
	s_add_u32 s26, s24, 0x1400
	s_addc_u32 s27, s25, 0
	s_add_u32 s30, s24, 0x2400
	s_addc_u32 s31, s25, 0
	global_atomic_add v0, v1, s[26:27]
	s_cmp_lg_u32 s101, 0
	s_cbranch_scc1 .Lxbn3_fol
	s_mul_i32 s21, s98, s99
	s_mov_b32 s22, 0

.Lxbn3_end:
.LBB0_1083:
	s_or_b64 exec, exec, s[4:5]
	s_mov_b64 s[52:53], s[0:1]
	s_waitcnt lgkmcnt(0)
	v_mov_b32_e32 v0, v170
	s_barrier
	s_movk_i32 s4, 0x1800
	v_ashrrev_i32_e32 v1, 6, v0
	v_add_u32_e32 v133, s46, v1
	v_cmp_gt_i32_e32 vcc, s4, v133
	s_and_saveexec_b64 s[54:55], vcc
	s_cbranch_execz .LBB0_1118
	s_load_dwordx2 s[6:7], s[52:53], 0xe8
	v_and_b32_e32 v4, 63, v0
	v_mov_b32_e32 v121, 0
	s_movk_i32 s4, 0x4400
	v_lshlrev_b32_e32 v122, 4, v4
	s_waitcnt lgkmcnt(0)
	s_add_u32 s56, s6, 0x9f9c000
	v_mov_b32_e32 v123, v121
	v_bfe_u32 v5, v0, 4, 2
	v_mul_lo_u32 v1, v1, s4
	s_addc_u32 s57, s7, 0
	v_lshl_add_u64 v[2:3], s[6:7], 0, v[122:123]
	s_mov_b64 s[8:9], 0x76d8000
	v_lshrrev_b32_e32 v6, 6, v0
	v_and_b32_e32 v177, 15, v0
	v_add_u32_e32 v1, 0, v1
	v_lshlrev_b32_e32 v120, 3, v5
	s_add_u32 s58, s6, 0x76c8000
	v_lshl_add_u64 v[124:125], v[2:3], 0, s[8:9]
	s_mov_b64 s[8:9], 0x7758000
	v_lshlrev_b32_e32 v128, 3, v4
	v_mov_b32_e32 v129, v121
	v_and_b32_e32 v0, 48, v0
	v_cmp_gt_u32_e64 s[4:5], 32, v4
	s_addc_u32 s59, s7, 0
	v_lshl_add_u64 v[126:127], v[2:3], 0, s[8:9]
	v_lshl_add_u64 v[2:3], s[6:7], 0, v[128:129]
	v_lshlrev_b32_e32 v132, 1, v4
	v_add_u32_e32 v8, v1, v0
	v_lshlrev_b32_e32 v0, 2, v5
	v_lshl_add_u64 v[4:5], s[6:7], 0, v[120:121]
	s_mov_b64 s[6:7], 0xbd9c000
	s_mov_b64 s[8:9], 0xb79c000
	v_add_u32_e32 v7, v1, v120
	v_mul_u32_u24_e32 v9, 0x110, v177
	v_lshl_add_u64 v[134:135], v[4:5], 0, s[6:7]
	s_mov_b64 s[6:7], 0xb79c200
	s_mov_b32 s64, 0xfff80000
	v_lshl_add_u64 v[130:131], v[2:3], 0, s[8:9]
	v_add_u32_e32 v123, v1, v132
	v_add_u16_e32 v178, s46, v6
	v_lshl_add_u64 v[136:137], v[2:3], 0, s[6:7]
	s_mov_b64 s[60:61], 0
	v_lshlrev_b32_e32 v138, 2, v120
	s_movk_i32 s45, 0x1000
	s_mov_b64 s[62:63], 0x80000
	s_mov_b32 s65, -1
	v_lshlrev_b32_e32 v140, 2, v0
	s_movk_i32 s47, 0x17ff
	v_mov_b32_e32 v139, v121
	v_add_u32_e32 v179, v7, v9
	v_add_u32_e32 v180, v8, v9
	s_branch .LBB0_1086

.LBB0_1118:
	s_or_b64 exec, exec, s[54:55]
	s_mov_b64 s[6:7], s[0:1]
	s_getreg_b32 s8, hwreg(HW_REG_XCC_ID, 0, 4)
	s_waitcnt vmcnt(0)
	s_barrier
	s_and_saveexec_b64 s[4:5], s[38:39]
	s_cbranch_execz .LBB0_1170
	s_and_b32 s20, s8, 15
	s_load_dwordx2 s[18:19], s[0:1], 0xe8
	s_add_i32 s98, s98, 1
	s_lshl_b32 s20, s20, 8
	v_mov_b32_e32 v0, 0
	v_mov_b32_e32 v1, 1
	s_waitcnt lgkmcnt(0)
	s_add_u32 s18, s18, 0x7798000
	s_addc_u32 s19, s19, 0
	s_add_u32 s24, s18, s20
	s_addc_u32 s25, s19, 0
	s_add_u32 s26, s24, 0x1400
	s_addc_u32 s27, s25, 0
	s_add_u32 s30, s24, 0x2400
	s_addc_u32 s31, s25, 0
	global_atomic_add v0, v1, s[26:27]
	s_cmp_lg_u32 s101, 0
	s_cbranch_scc1 .Lxbn4_fol
	s_mul_i32 s21, s98, s99
	s_mov_b32 s22, 0

.Lxbn4_end:
.LBB0_1170:
	s_or_b64 exec, exec, s[4:5]
	s_mov_b64 s[4:5], s[0:1]
	v_mov_b32_e32 v8, v170
	s_waitcnt lgkmcnt(0)
	s_barrier
	s_cmpk_gt_i32 s2, 0x5f
	v_readfirstlane_b32 s30, v8
	s_cbranch_scc1 .LBB0_1182
	v_lshlrev_b32_e32 v0, 4, v8
	v_add_u32_e32 v1, 0x2000, v0
	v_ashrrev_i32_e32 v2, 31, v1
	v_lshrrev_b32_e32 v2, 22, v2
	v_add_u32_e32 v2, v1, v2
	v_ashrrev_i32_e32 v9, 10, v2
	v_mul_i32_i24_e32 v3, 0x400, v9
	v_sub_u32_e32 v1, v1, v3
	v_lshrrev_b32_e32 v3, 4, v1
	s_load_dwordx2 s[12:13], s[4:5], 0xe8
	v_bitop3_b32 v1, v3, v1, 32 bitop3:0x6c
	v_ashrrev_i32_e32 v3, 31, v1
	v_lshrrev_b32_e32 v3, 26, v3
	v_add_u32_e32 v3, v1, v3
	v_ashrrev_i32_e32 v10, 6, v3
	v_and_b32_e32 v3, 0xc0, v3
	s_waitcnt lgkmcnt(0)
	s_add_u32 s31, s12, 0xdbc000
	v_sub_u32_e32 v1, v1, v3
	v_mov_b32_e32 v3, 1
	s_addc_u32 s34, s13, 0
	v_lshlrev_b32_e32 v2, 5, v9
	v_ashrrev_i16_sdwa v1, v3, sext(v1) dst_sel:DWORD dst_unused:UNUSED_PAD src0_sel:DWORD src1_sel:BYTE_0
	s_add_u32 s14, s12, 0xbd9c000
	v_and_b32_e32 v2, 32, v2
	v_bfe_i32 v11, v1, 0, 16
	s_addc_u32 s15, s13, 0
	v_add_u32_e32 v1, v2, v11
	v_lshlrev_b32_e32 v2, 3, v9
	s_lshr_b32 s4, s3, 29
	v_and_b32_e32 v2, 0x3ffff0, v2
	s_add_i32 s4, s2, s4
	v_add_lshl_u32 v2, v10, v2, 10
	s_ashr_i32 s6, s4, 3
	s_and_b32 s4, s4, -8
	v_lshl_add_u32 v128, v1, 1, v2
	v_bfe_i32 v2, v8, 27, 1
	s_sub_i32 s4, s2, s4
	v_lshrrev_b32_e32 v2, 22, v2
	s_lshr_b32 s7, s4, 31
	v_add_u32_e32 v2, v0, v2
	s_or_b32 s7, s7, 12
	v_and_b32_e32 v2, 0xfffffc00, v2
	s_mul_i32 s4, s7, s4
	v_sub_u32_e32 v0, v0, v2
	s_add_i32 s4, s4, s6
	v_lshrrev_b32_e32 v2, 4, v0
	s_ashr_i32 s6, s4, 31
	v_bitop3_b32 v2, v2, v0, 32 bitop3:0x6c
	v_ashrrev_i32_e32 v0, 31, v0
	s_lshr_b32 s6, s6, 28
	v_lshrrev_b32_e32 v0, 26, v0
	s_add_i32 s6, s4, s6
	v_ashrrev_i32_e32 v1, 31, v8
	v_add_u32_e32 v0, v2, v0
	s_ashr_i32 s6, s6, 4
	v_lshrrev_b32_e32 v1, 26, v1
	v_ashrrev_i32_e32 v13, 6, v0
	s_lshl_b32 s8, s6, 3
	v_add_u32_e32 v1, v8, v1
	v_mul_i32_i24_e32 v0, 64, v13
	s_sub_i32 s7, 48, s8
	s_lshl_b32 s6, s6, 4
	v_ashrrev_i32_e32 v12, 6, v1
	v_sub_u32_e32 v0, v2, v0
	s_min_u32 s9, s7, 8
	s_sub_i32 s10, s4, s6
	v_lshlrev_b32_e32 v1, 5, v12
	v_ashrrev_i16_sdwa v0, v3, sext(v0) dst_sel:DWORD dst_unused:UNUSED_PAD src0_sel:DWORD src1_sel:BYTE_0
	s_sext_i32_i8 s4, s10
	v_cvt_f32_ubyte0_e32 v3, s9
	v_and_b32_e32 v1, 32, v1
	v_bfe_i32 v14, v0, 0, 16
	v_cvt_f32_i32_e32 v2, s4
	v_rcp_iflag_f32_e32 v4, v3
	v_add_u32_e32 v0, v1, v14
	v_lshlrev_b32_e32 v1, 3, v12
	v_and_b32_e32 v1, 0x3ffff0, v1
	v_add_lshl_u32 v1, v13, v1, 10
	v_lshl_add_u32 v130, v0, 1, v1
	v_mul_f32_e32 v0, v2, v4
	v_trunc_f32_e32 v0, v0
	v_fma_f32 v1, -v0, v3, v2
	v_cvt_i32_f32_e32 v0, v0
	s_ashr_i32 s16, s30, 6
	s_ashr_i32 s4, s4, 30
	s_ashr_i32 s5, s30, 8
	s_lshl_b32 s35, s16, 10
	s_or_b32 s4, s4, 1
	v_cmp_ge_f32_e64 s[6:7], |v1|, v3
	s_and_b64 s[6:7], s[6:7], exec
	s_cselect_b32 s4, s4, 0
	v_readfirstlane_b32 s6, v0
	s_add_i32 s4, s6, s4
	s_mul_i32 s6, s4, s9
	s_sub_i32 s6, s10, s6
	s_sext_i32_i8 s6, s6
	s_add_i32 s6, s8, s6
	s_ashr_i32 s7, s6, 31
	s_bfe_i64 s[8:9], s[4:5], 0x80000
	s_lshl_b64 s[10:11], s[6:7], 18
	s_lshl_b64 s[8:9], s[8:9], 18
	s_add_u32 s8, s31, s8
	s_addc_u32 s9, s34, s9
	s_add_i32 s36, s35, 0
	s_add_i32 m0, s36, 0x10000
	v_mov_b32_e32 v131, 0
	global_load_lds_dwordx4 v130, s[8:9]
	s_add_i32 m0, s36, 0x12000
	s_add_u32 s10, s14, s10
	global_load_lds_dwordx4 v128, s[8:9]
	s_addc_u32 s11, s15, s11
	s_mov_b32 m0, s36
	s_add_i32 s37, s36, 0x2000
	global_load_lds_dwordx4 v130, s[10:11]
	s_mov_b32 m0, s37
	s_add_u32 s18, s8, 0x20000
	global_load_lds_dwordx4 v128, s[10:11]
	s_addc_u32 s19, s9, 0
	s_add_i32 m0, s36, 0x14000
	v_mov_b32_e32 v129, v131
	global_load_lds_dwordx4 v130, s[18:19]
	s_add_i32 m0, s36, 0x16000
	s_mov_b32 s45, 0
	global_load_lds_dwordx4 v128, s[18:19]
	s_add_u32 s18, s10, 0x20000
	s_addc_u32 s19, s11, 0
	s_add_i32 s40, s36, 0x4000
	s_mov_b32 m0, s40
	s_add_i32 s41, s36, 0x6000
	global_load_lds_dwordx4 v130, s[18:19]
	s_mov_b32 m0, s41
	v_lshl_add_u64 v[6:7], s[8:9], 0, v[130:131]
	global_load_lds_dwordx4 v128, s[18:19]
	v_lshl_add_u64 v[4:5], s[8:9], 0, v[128:129]
	v_lshl_add_u64 v[2:3], s[10:11], 0, v[130:131]
	s_cmp_lg_u32 s5, 1
	v_lshl_add_u64 v[0:1], s[10:11], 0, v[128:129]
	s_cbranch_scc1 .LBB0_1173
	s_barrier

.LBB0_1182:
	s_mov_b64 s[6:7], s[0:1]
	s_getreg_b32 s8, hwreg(HW_REG_XCC_ID, 0, 4)
	s_waitcnt vmcnt(0)
	s_waitcnt lgkmcnt(0)
	s_barrier
	s_and_saveexec_b64 s[4:5], s[38:39]
	s_cbranch_execz .LBB0_1234
	s_and_b32 s20, s8, 15
	s_load_dwordx2 s[18:19], s[0:1], 0xe8
	s_add_i32 s98, s98, 1
	s_lshl_b32 s20, s20, 8
	v_mov_b32_e32 v0, 0
	v_mov_b32_e32 v1, 1
	s_waitcnt lgkmcnt(0)
	s_add_u32 s18, s18, 0x7798000
	s_addc_u32 s19, s19, 0
	s_add_u32 s24, s18, s20
	s_addc_u32 s25, s19, 0
	s_add_u32 s26, s24, 0x1400
	s_addc_u32 s27, s25, 0
	s_add_u32 s30, s24, 0x2400
	s_addc_u32 s31, s25, 0
	global_atomic_add v0, v1, s[26:27]
	s_cmp_lg_u32 s101, 0
	s_cbranch_scc1 .Lxbn5_fol
	s_mul_i32 s21, s98, s99
	s_mov_b32 s22, 0

.Lxbn5_end:
.LBB0_1234:
	s_or_b64 exec, exec, s[4:5]
	s_mov_b64 s[6:7], s[0:1]
	s_waitcnt lgkmcnt(0)
	s_barrier
	s_load_dwordx2 s[8:9], s[6:7], 0xe8
	v_mov_b32_e32 v8, v170
	s_waitcnt lgkmcnt(0)
	s_add_u32 s12, s8, 0x46bc000
	s_addc_u32 s13, s9, 0
	s_cmpk_lt_i32 s2, 0xc0
	s_cselect_b64 s[14:15], -1, 0
	s_cmpk_gt_i32 s2, 0xbf
	v_readfirstlane_b32 s45, v8
	s_cbranch_scc1 .LBB0_1246
	v_lshlrev_b32_e32 v0, 4, v8
	v_add_u32_e32 v1, 0x2000, v0
	v_ashrrev_i32_e32 v2, 31, v1
	v_lshrrev_b32_e32 v2, 22, v2
	v_add_u32_e32 v2, v1, v2
	v_ashrrev_i32_e32 v9, 10, v2
	v_mul_i32_i24_e32 v3, 0x400, v9
	v_sub_u32_e32 v1, v1, v3
	v_lshrrev_b32_e32 v3, 4, v1
	v_bitop3_b32 v1, v3, v1, 32 bitop3:0x6c
	v_ashrrev_i32_e32 v3, 31, v1
	v_lshrrev_b32_e32 v3, 26, v3
	v_add_u32_e32 v3, v1, v3
	v_ashrrev_i32_e32 v10, 6, v3
	v_and_b32_e32 v3, 0xc0, v3
	s_add_u32 s47, s8, 0xbbc000
	v_sub_u32_e32 v1, v1, v3
	v_mov_b32_e32 v3, 1
	s_addc_u32 s54, s9, 0
	v_lshlrev_b32_e32 v2, 5, v9
	v_ashrrev_i16_sdwa v1, v3, sext(v1) dst_sel:DWORD dst_unused:UNUSED_PAD src0_sel:DWORD src1_sel:BYTE_0
	s_add_u32 s55, s8, 0xc99c000
	v_and_b32_e32 v2, 32, v2
	v_bfe_i32 v11, v1, 0, 16
	s_addc_u32 s56, s9, 0
	v_add_u32_e32 v1, v2, v11
	v_lshlrev_b32_e32 v2, 3, v9
	s_lshr_b32 s4, s3, 29
	v_and_b32_e32 v2, 0x1ffff0, v2
	s_add_i32 s4, s2, s4
	v_add_lshl_u32 v2, v10, v2, 11
	s_ashr_i32 s10, s4, 3
	s_and_b32 s4, s4, -8
	v_lshl_add_u32 v128, v1, 1, v2
	v_bfe_i32 v2, v8, 27, 1
	s_sub_i32 s4, s2, s4
	v_lshrrev_b32_e32 v2, 22, v2
	s_lshr_b32 s11, s4, 31
	v_add_u32_e32 v2, v0, v2
	s_or_b32 s11, s11, 24
	v_and_b32_e32 v2, 0xfffffc00, v2
	s_mul_i32 s4, s11, s4
	v_sub_u32_e32 v0, v0, v2
	s_add_i32 s4, s4, s10
	v_lshrrev_b32_e32 v2, 4, v0
	s_ashr_i32 s10, s4, 31
	v_bitop3_b32 v2, v2, v0, 32 bitop3:0x6c
	v_ashrrev_i32_e32 v0, 31, v0
	s_lshr_b32 s10, s10, 27
	v_lshrrev_b32_e32 v0, 26, v0
	s_add_i32 s10, s4, s10
	v_ashrrev_i32_e32 v1, 31, v8
	v_add_u32_e32 v0, v2, v0
	s_ashr_i32 s10, s10, 5
	v_lshrrev_b32_e32 v1, 26, v1
	v_ashrrev_i32_e32 v13, 6, v0
	s_lshl_b32 s17, s10, 3
	v_add_u32_e32 v1, v8, v1
	v_mul_i32_i24_e32 v0, 64, v13
	s_sub_i32 s11, 48, s17
	s_lshl_b32 s10, s10, 5
	v_ashrrev_i32_e32 v12, 6, v1
	v_sub_u32_e32 v0, v2, v0
	s_min_u32 s18, s11, 8
	s_sub_i32 s19, s4, s10
	v_lshlrev_b32_e32 v1, 5, v12
	v_ashrrev_i16_sdwa v0, v3, sext(v0) dst_sel:DWORD dst_unused:UNUSED_PAD src0_sel:DWORD src1_sel:BYTE_0
	s_sext_i32_i8 s4, s19
	v_cvt_f32_ubyte0_e32 v3, s18
	v_and_b32_e32 v1, 32, v1
	v_bfe_i32 v14, v0, 0, 16
	v_cvt_f32_i32_e32 v2, s4
	v_rcp_iflag_f32_e32 v4, v3
	v_add_u32_e32 v0, v1, v14
	v_lshlrev_b32_e32 v1, 3, v12
	v_and_b32_e32 v1, 0x1ffff0, v1
	v_add_lshl_u32 v1, v13, v1, 11
	v_lshl_add_u32 v130, v0, 1, v1
	v_mul_f32_e32 v0, v2, v4
	v_trunc_f32_e32 v0, v0
	v_fma_f32 v1, -v0, v3, v2
	v_cvt_i32_f32_e32 v0, v0
	s_ashr_i32 s16, s45, 6
	s_ashr_i32 s4, s4, 30
	s_ashr_i32 s5, s45, 8
	s_lshl_b32 s57, s16, 10
	s_or_b32 s4, s4, 1
	v_cmp_ge_f32_e64 s[10:11], |v1|, v3
	s_and_b64 s[10:11], s[10:11], exec
	s_cselect_b32 s4, s4, 0
	v_readfirstlane_b32 s10, v0
	s_add_i32 s4, s10, s4
	s_mul_i32 s10, s4, s18
	s_sub_i32 s10, s19, s10
	s_sext_i32_i8 s10, s10
	s_add_i32 s10, s17, s10
	s_ashr_i32 s11, s10, 31
	s_bfe_i64 s[20:21], s[4:5], 0x80000
	s_lshl_b64 s[18:19], s[10:11], 19
	s_lshl_b64 s[20:21], s[20:21], 19
	s_add_u32 s36, s47, s20
	s_addc_u32 s37, s54, s21
	s_add_i32 s58, s57, 0
	s_add_i32 m0, s58, 0x10000
	v_mov_b32_e32 v133, 0
	global_load_lds_dwordx4 v130, s[36:37]
	s_add_i32 m0, s58, 0x12000
	s_add_u32 s40, s55, s18
	global_load_lds_dwordx4 v128, s[36:37]
	s_addc_u32 s41, s56, s19
	s_mov_b32 m0, s58
	s_add_i32 s59, s58, 0x2000
	global_load_lds_dwordx4 v130, s[40:41]
	s_mov_b32 m0, s59
	s_add_u32 s18, s36, 0x40000
	global_load_lds_dwordx4 v128, s[40:41]
	s_addc_u32 s19, s37, 0
	s_add_i32 m0, s58, 0x14000
	v_mov_b32_e32 v131, v133
	global_load_lds_dwordx4 v130, s[18:19]
	s_add_i32 m0, s58, 0x16000
	v_mov_b32_e32 v129, v133
	global_load_lds_dwordx4 v128, s[18:19]
	s_add_u32 s18, s40, 0x40000
	s_addc_u32 s19, s41, 0
	s_add_i32 s60, s58, 0x4000
	s_mov_b32 m0, s60
	s_add_i32 s61, s58, 0x6000
	global_load_lds_dwordx4 v130, s[18:19]
	s_mov_b32 m0, s61
	s_mov_b32 s11, 0
	global_load_lds_dwordx4 v128, s[18:19]
	v_lshl_add_u64 v[6:7], s[36:37], 0, v[130:131]
	v_lshl_add_u64 v[4:5], s[36:37], 0, v[128:129]
	v_lshl_add_u64 v[2:3], s[40:41], 0, v[130:131]
	s_cmp_lg_u32 s5, 1
	v_lshl_add_u64 v[0:1], s[40:41], 0, v[128:129]
	s_cbranch_scc1 .LBB0_1237
	s_barrier

.LBB0_1337:
	s_mov_b64 s[10:11], s[0:1]
	s_getreg_b32 s12, hwreg(HW_REG_XCC_ID, 0, 4)
	s_waitcnt vmcnt(0)
	s_waitcnt lgkmcnt(0)
	s_barrier
	s_and_saveexec_b64 s[8:9], s[38:39]
	s_cbranch_execz .LBB0_1389
	s_and_b32 s20, s12, 15
	s_load_dwordx2 s[18:19], s[0:1], 0xe8
	s_add_i32 s98, s98, 1
	s_lshl_b32 s20, s20, 8
	v_mov_b32_e32 v0, 0
	v_mov_b32_e32 v1, 1
	s_waitcnt lgkmcnt(0)
	s_add_u32 s18, s18, 0x7798000
	s_addc_u32 s19, s19, 0
	s_add_u32 s24, s18, s20
	s_addc_u32 s25, s19, 0
	s_add_u32 s26, s24, 0x1400
	s_addc_u32 s27, s25, 0
	s_add_u32 s30, s24, 0x2400
	s_addc_u32 s31, s25, 0
	global_atomic_add v0, v1, s[26:27]
	s_cmp_lg_u32 s101, 0
	s_cbranch_scc1 .Lxbn6_fol
	s_mul_i32 s21, s98, s99
	s_mov_b32 s22, 0

.Lxbn6_end:
.LBB0_1389:
	s_or_b64 exec, exec, s[8:9]
	s_waitcnt lgkmcnt(0)
	v_cndmask_b32_e64 v0, 0, 1, s[50:51]
	s_mov_b64 s[10:11], s[0:1]
	v_mov_b32_e32 v8, v170
	v_cmp_ne_u32_e64 s[8:9], 1, v0
	s_barrier
	s_nop 0
	v_writelane_b32 v234, s8, 0
	s_andn2_b64 vcc, exec, s[50:51]
	v_readfirstlane_b32 s45, v8
	v_writelane_b32 v234, s9, 1
	s_cbranch_vccnz .LBB0_1401
	v_lshlrev_b32_e32 v0, 4, v8
	v_add_u32_e32 v1, 0x2000, v0
	v_ashrrev_i32_e32 v2, 31, v1
	v_lshrrev_b32_e32 v2, 22, v2
	v_add_u32_e32 v2, v1, v2
	v_ashrrev_i32_e32 v9, 10, v2
	v_mul_i32_i24_e32 v3, 0x400, v9
	v_sub_u32_e32 v1, v1, v3
	v_lshrrev_b32_e32 v3, 4, v1
	s_load_dwordx2 s[10:11], s[10:11], 0xe8
	v_bitop3_b32 v1, v3, v1, 32 bitop3:0x6c
	v_ashrrev_i32_e32 v3, 31, v1
	v_lshrrev_b32_e32 v3, 26, v3
	v_add_u32_e32 v3, v1, v3
	v_ashrrev_i32_e32 v10, 6, v3
	v_and_b32_e32 v3, 0xc0, v3
	s_waitcnt lgkmcnt(0)
	s_add_u32 s47, s10, 0xebc000
	v_sub_u32_e32 v1, v1, v3
	v_mov_b32_e32 v3, 1
	s_addc_u32 s50, s11, 0
	v_lshlrev_b32_e32 v2, 5, v9
	v_ashrrev_i16_sdwa v1, v3, sext(v1) dst_sel:DWORD dst_unused:UNUSED_PAD src0_sel:DWORD src1_sel:BYTE_0
	s_add_u32 s51, s10, 0x2ebc000
	v_and_b32_e32 v2, 32, v2
	v_bfe_i32 v11, v1, 0, 16
	s_addc_u32 s52, s11, 0
	v_add_u32_e32 v1, v2, v11
	v_lshlrev_b32_e32 v2, 3, v9
	s_lshr_b32 s16, s3, 29
	v_and_b32_e32 v2, 0x1ffff0, v2
	s_add_i32 s16, s2, s16
	v_add_lshl_u32 v2, v10, v2, 11
	s_ashr_i32 s17, s16, 3
	s_and_b32 s16, s16, -8
	v_lshl_add_u32 v128, v1, 1, v2
	v_bfe_i32 v2, v8, 27, 1
	s_sub_i32 s16, s2, s16
	v_lshrrev_b32_e32 v2, 22, v2
	s_lshr_b32 s18, s16, 31
	v_add_u32_e32 v2, v0, v2
	s_or_b32 s18, s18, 0x60
	v_and_b32_e32 v2, 0xfffffc00, v2
	s_mul_i32 s16, s18, s16
	v_sub_u32_e32 v0, v0, v2
	s_add_i32 s16, s16, s17
	v_lshrrev_b32_e32 v2, 4, v0
	s_ashr_i32 s17, s16, 31
	v_bitop3_b32 v2, v2, v0, 32 bitop3:0x6c
	v_ashrrev_i32_e32 v0, 31, v0
	s_lshr_b32 s17, s17, 25
	v_lshrrev_b32_e32 v0, 26, v0
	s_add_i32 s17, s16, s17
	v_ashrrev_i32_e32 v1, 31, v8
	v_add_u32_e32 v0, v2, v0
	s_ashr_i32 s17, s17, 7
	v_lshrrev_b32_e32 v1, 26, v1
	v_ashrrev_i32_e32 v13, 6, v0
	s_lshl_b32 s18, s17, 3
	v_add_u32_e32 v1, v8, v1
	v_mul_i32_i24_e32 v0, 64, v13
	s_sub_i32 s19, 48, s18
	s_lshl_b32 s17, s17, 7
	v_ashrrev_i32_e32 v12, 6, v1
	v_sub_u32_e32 v0, v2, v0
	s_min_u32 s19, s19, 8
	s_sub_i32 s20, s16, s17
	v_lshlrev_b32_e32 v1, 5, v12
	v_ashrrev_i16_sdwa v0, v3, sext(v0) dst_sel:DWORD dst_unused:UNUSED_PAD src0_sel:DWORD src1_sel:BYTE_0
	s_sext_i32_i8 s16, s20
	v_cvt_f32_ubyte0_e32 v3, s19
	v_and_b32_e32 v1, 32, v1
	v_bfe_i32 v14, v0, 0, 16
	v_cvt_f32_i32_e32 v2, s16
	v_rcp_iflag_f32_e32 v4, v3
	v_add_u32_e32 v0, v1, v14
	v_lshlrev_b32_e32 v1, 3, v12
	v_and_b32_e32 v1, 0x1ffff0, v1
	v_add_lshl_u32 v1, v13, v1, 11
	v_lshl_add_u32 v130, v0, 1, v1
	v_mul_f32_e32 v0, v2, v4
	v_trunc_f32_e32 v0, v0
	v_fma_f32 v1, -v0, v3, v2
	v_cvt_i32_f32_e32 v0, v0
	s_ashr_i32 s13, s45, 6
	s_ashr_i32 s16, s16, 30
	s_ashr_i32 s12, s45, 8
	s_lshl_b32 s53, s13, 10
	s_or_b32 s21, s16, 1
	v_cmp_ge_f32_e64 s[16:17], |v1|, v3
	s_and_b64 s[16:17], s[16:17], exec
	s_cselect_b32 s16, s21, 0
	v_readfirstlane_b32 s17, v0
	s_add_i32 s16, s17, s16
	s_mul_i32 s17, s16, s19
	s_sub_i32 s17, s20, s17
	s_sext_i32_i8 s17, s17
	s_add_i32 s30, s18, s17
	s_ashr_i32 s31, s30, 31
	s_bfe_i64 s[20:21], s[16:17], 0x80000
	s_lshl_b64 s[18:19], s[30:31], 19
	s_lshl_b64 s[20:21], s[20:21], 19
	s_add_u32 s34, s47, s20
	s_addc_u32 s35, s50, s21
	s_add_i32 s54, s53, 0
	s_add_i32 m0, s54, 0x10000
	v_mov_b32_e32 v133, 0
	global_load_lds_dwordx4 v130, s[34:35]
	s_add_i32 m0, s54, 0x12000
	s_add_u32 s36, s51, s18
	global_load_lds_dwordx4 v128, s[34:35]
	s_addc_u32 s37, s52, s19
	s_mov_b32 m0, s54
	s_add_i32 s55, s54, 0x2000
	global_load_lds_dwordx4 v130, s[36:37]
	s_mov_b32 m0, s55
	s_add_u32 s18, s34, 0x40000
	global_load_lds_dwordx4 v128, s[36:37]
	s_addc_u32 s19, s35, 0
	s_add_i32 m0, s54, 0x14000
	v_mov_b32_e32 v131, v133
	global_load_lds_dwordx4 v130, s[18:19]
	s_add_i32 m0, s54, 0x16000
	v_mov_b32_e32 v129, v133
	global_load_lds_dwordx4 v128, s[18:19]
	s_add_u32 s18, s36, 0x40000
	s_addc_u32 s19, s37, 0
	s_add_i32 s56, s54, 0x4000
	s_mov_b32 m0, s56
	s_add_i32 s57, s54, 0x6000
	global_load_lds_dwordx4 v130, s[18:19]
	s_mov_b32 m0, s57
	s_mov_b32 s58, 0
	global_load_lds_dwordx4 v128, s[18:19]
	v_lshl_add_u64 v[6:7], s[34:35], 0, v[130:131]
	v_lshl_add_u64 v[4:5], s[34:35], 0, v[128:129]
	v_lshl_add_u64 v[2:3], s[36:37], 0, v[130:131]
	s_cmp_lg_u32 s12, 1
	v_lshl_add_u64 v[0:1], s[36:37], 0, v[128:129]
	s_cbranch_scc1 .LBB0_1392
	s_barrier

.LBB0_1401:
	s_mov_b64 s[12:13], s[0:1]
	s_getreg_b32 s16, hwreg(HW_REG_XCC_ID, 0, 4)
	s_waitcnt vmcnt(0)
	s_waitcnt vmcnt(0) lgkmcnt(0)
	s_barrier
	s_and_saveexec_b64 s[10:11], s[38:39]
	s_cbranch_execz .LBB0_1453
	s_and_b32 s20, s16, 15
	s_load_dwordx2 s[18:19], s[0:1], 0xe8
	s_add_i32 s98, s98, 1
	s_lshl_b32 s20, s20, 8
	v_mov_b32_e32 v0, 0
	v_mov_b32_e32 v1, 1
	s_waitcnt lgkmcnt(0)
	s_add_u32 s18, s18, 0x7798000
	s_addc_u32 s19, s19, 0
	s_add_u32 s24, s18, s20
	s_addc_u32 s25, s19, 0
	s_add_u32 s26, s24, 0x1400
	s_addc_u32 s27, s25, 0
	s_add_u32 s30, s24, 0x2400
	s_addc_u32 s31, s25, 0
	global_atomic_add v0, v1, s[26:27]
	s_cmp_lg_u32 s101, 0
	s_cbranch_scc1 .Lxbn7_fol
	s_mul_i32 s21, s98, s99
	s_mov_b32 s22, 0

.Lxbn7_end:
.LBB0_1453:
	s_or_b64 exec, exec, s[10:11]
	s_mov_b64 s[20:21], s[0:1]
	s_waitcnt lgkmcnt(0)
	s_barrier
	s_load_dwordx2 s[22:23], s[20:21], 0xe8
	v_mov_b32_e32 v4, v170
	v_cndmask_b32_e64 v0, 0, 1, s[14:15]
	v_cmp_ne_u32_e64 s[10:11], 1, v0
	s_waitcnt lgkmcnt(0)
	s_add_u32 s24, s22, 0x46bc000
	s_addc_u32 s25, s23, 0
	s_add_u32 s45, s22, 0x1ebc000
	s_addc_u32 s47, s23, 0
	s_andn2_b64 vcc, exec, s[14:15]
	v_readfirstlane_b32 s60, v4
	s_cbranch_vccnz .LBB0_1466
	v_lshlrev_b32_e32 v0, 4, v4
	v_add_u32_e32 v1, 0x2000, v0
	v_ashrrev_i32_e32 v2, 31, v1
	v_lshrrev_b32_e32 v2, 22, v2
	v_add_u32_e32 v2, v1, v2
	v_ashrrev_i32_e32 v5, 10, v2
	v_mul_i32_i24_e32 v3, 0x400, v5
	v_sub_u32_e32 v1, v1, v3
	v_lshrrev_b32_e32 v3, 4, v1
	v_bitop3_b32 v1, v3, v1, 32 bitop3:0x6c
	v_ashrrev_i32_e32 v3, 31, v1
	v_lshrrev_b32_e32 v3, 26, v3
	v_add_u32_e32 v3, v1, v3
	v_ashrrev_i32_e32 v6, 6, v3
	v_and_b32_e32 v3, 0xc0, v3
	v_sub_u32_e32 v1, v1, v3
	v_mov_b32_e32 v3, 1
	v_lshlrev_b32_e32 v2, 5, v5
	v_ashrrev_i16_sdwa v1, v3, sext(v1) dst_sel:DWORD dst_unused:UNUSED_PAD src0_sel:DWORD src1_sel:BYTE_0
	v_and_b32_e32 v2, 32, v2
	v_bfe_i32 v7, v1, 0, 16
	v_add_u32_e32 v1, v2, v7
	v_lshlrev_b32_e32 v2, 3, v5
	v_and_b32_e32 v2, -16, v2
	v_add_u32_e32 v2, v6, v2
	v_lshlrev_b32_e32 v8, 13, v2
	v_lshl_add_u32 v128, v1, 1, v8
	s_movk_i32 s12, 0xe080
	v_mad_u64_u32 v[130:131], s[14:15], v2, s12, v[128:129]
	v_bfe_i32 v2, v4, 27, 1
	v_lshrrev_b32_e32 v2, 22, v2
	s_add_u32 s61, s22, 0x779c000
	v_add_u32_e32 v2, v0, v2
	s_addc_u32 s62, s23, 0
	v_and_b32_e32 v2, 0xfffffc00, v2
	s_lshr_b32 s14, s3, 29
	v_sub_u32_e32 v0, v0, v2
	s_add_i32 s14, s2, s14
	v_lshrrev_b32_e32 v2, 4, v0
	s_ashr_i32 s15, s14, 3
	s_and_b32 s14, s14, -8
	v_bitop3_b32 v2, v2, v0, 32 bitop3:0x6c
	v_ashrrev_i32_e32 v0, 31, v0
	s_sub_i32 s14, s2, s14
	v_lshrrev_b32_e32 v0, 26, v0
	s_lshr_b32 s17, s14, 31
	v_ashrrev_i32_e32 v1, 31, v4
	v_add_u32_e32 v0, v2, v0
	s_or_b32 s17, s17, 24
	v_lshrrev_b32_e32 v1, 26, v1
	v_ashrrev_i32_e32 v9, 6, v0
	s_mul_i32 s14, s17, s14
	v_add_u32_e32 v1, v4, v1
	v_mul_i32_i24_e32 v0, 64, v9
	s_add_i32 s14, s14, s15
	v_ashrrev_i32_e32 v8, 6, v1
	v_sub_u32_e32 v0, v2, v0
	s_ashr_i32 s15, s14, 31
	v_lshlrev_b32_e32 v1, 5, v8
	v_ashrrev_i16_sdwa v0, v3, sext(v0) dst_sel:DWORD dst_unused:UNUSED_PAD src0_sel:DWORD src1_sel:BYTE_0
	s_lshr_b32 s15, s15, 27
	v_and_b32_e32 v1, 32, v1
	v_bfe_i32 v10, v0, 0, 16
	s_add_i32 s15, s14, s15
	v_add_u32_e32 v0, v1, v10
	v_lshlrev_b32_e32 v1, 3, v8
	s_ashr_i32 s15, s15, 5
	v_and_b32_e32 v1, -16, v1
	s_lshl_b32 s17, s15, 3
	v_add_u32_e32 v1, v9, v1
	s_sub_i32 s18, 48, s17
	s_lshl_b32 s15, s15, 5
	v_lshlrev_b32_e32 v2, 13, v1
	s_min_u32 s18, s18, 8
	s_sub_i32 s19, s14, s15
	v_lshl_add_u32 v132, v0, 1, v2
	s_sext_i32_i8 s26, s19
	v_cvt_f32_ubyte0_e32 v2, s18
	v_cvt_f32_i32_e32 v0, s26
	v_rcp_iflag_f32_e32 v3, v2
	v_mad_u64_u32 v[134:135], s[14:15], v1, s12, v[132:133]
	s_ashr_i32 s16, s60, 6
	v_mul_f32_e32 v1, v0, v3
	v_trunc_f32_e32 v1, v1
	v_fma_f32 v0, -v1, v2, v0
	v_cvt_i32_f32_e32 v1, v1
	s_ashr_i32 s12, s26, 30
	s_ashr_i32 s13, s60, 8
	s_lshl_b32 s63, s16, 10
	s_or_b32 s12, s12, 1
	v_cmp_ge_f32_e64 s[14:15], |v0|, v2
	s_and_b64 s[14:15], s[14:15], exec
	s_cselect_b32 s12, s12, 0
	v_readfirstlane_b32 s14, v1
	s_add_i32 s12, s14, s12
	s_mul_i32 s14, s12, s18
	s_sub_i32 s14, s19, s14
	s_sext_i32_i8 s14, s14
	s_add_i32 s14, s17, s14
	s_ashr_i32 s15, s14, 31
	s_bfe_i64 s[26:27], s[12:13], 0x80000
	s_lshl_b64 s[18:19], s[14:15], 21
	s_lshl_b64 s[26:27], s[26:27], 21
	s_add_u32 s52, s45, s26
	s_addc_u32 s53, s47, s27
	s_add_i32 s64, s63, 0
	s_add_i32 m0, s64, 0x10000
	v_mov_b32_e32 v133, 0
	global_load_lds_dwordx4 v132, s[52:53]
	s_add_i32 m0, s64, 0x12000
	s_add_u32 s54, s61, s18
	global_load_lds_dwordx4 v128, s[52:53]
	s_addc_u32 s55, s62, s19
	s_mov_b32 m0, s64
	s_add_i32 s65, s64, 0x2000
	global_load_lds_dwordx4 v134, s[54:55]
	s_mov_b32 m0, s65
	s_add_u32 s18, s52, 0x100000
	global_load_lds_dwordx4 v130, s[54:55]
	s_addc_u32 s19, s53, 0
	s_add_i32 m0, s64, 0x14000
	v_mov_b32_e32 v129, v133
	global_load_lds_dwordx4 v132, s[18:19]
	s_add_i32 m0, s64, 0x16000
	s_mov_b64 s[8:9], s[6:7]
	global_load_lds_dwordx4 v128, s[18:19]
	s_add_u32 s18, s54, 0x4000
	s_addc_u32 s19, s55, 0
	s_add_i32 s66, s64, 0x4000
	s_mov_b32 m0, s66
	s_add_i32 s67, s64, 0x6000
	global_load_lds_dwordx4 v134, s[18:19]
	s_mov_b32 m0, s67
	s_mov_b64 s[6:7], s[88:89]
	global_load_lds_dwordx4 v130, s[18:19]
	s_mov_b32 s15, 0
	v_lshl_add_u64 v[2:3], s[52:53], 0, v[132:133]
	v_lshl_add_u64 v[0:1], s[52:53], 0, v[128:129]
	v_mov_b32_e32 v135, v133
	s_cmp_lg_u32 s13, 1
	v_mov_b32_e32 v131, v133
	s_cbranch_scc1 .LBB0_1456
	s_barrier

.LBB0_1584:
	s_mov_b64 s[14:15], s[0:1]
	s_getreg_b32 s16, hwreg(HW_REG_XCC_ID, 0, 4)
	s_waitcnt vmcnt(0)
	s_waitcnt lgkmcnt(0)
	s_barrier
	s_and_saveexec_b64 s[12:13], s[38:39]
	s_cbranch_execz .LBB0_1636
	s_and_b32 s20, s16, 15
	s_load_dwordx2 s[18:19], s[0:1], 0xe8
	s_add_i32 s98, s98, 1
	s_lshl_b32 s20, s20, 8
	v_mov_b32_e32 v0, 0
	v_mov_b32_e32 v1, 1
	s_waitcnt lgkmcnt(0)
	s_add_u32 s18, s18, 0x7798000
	s_addc_u32 s19, s19, 0
	s_add_u32 s24, s18, s20
	s_addc_u32 s25, s19, 0
	s_add_u32 s26, s24, 0x1400
	s_addc_u32 s27, s25, 0
	s_add_u32 s30, s24, 0x2400
	s_addc_u32 s31, s25, 0
	global_atomic_add v0, v1, s[26:27]
	s_cmp_lg_u32 s101, 0
	s_cbranch_scc1 .Lxbn8_fol
	s_mul_i32 s21, s98, s99
	s_mov_b32 s22, 0

.Lxbn8_end:
.LBB0_1636:
	s_or_b64 exec, exec, s[12:13]
	s_mov_b64 s[12:13], s[0:1]
	s_waitcnt lgkmcnt(0)
	v_mov_b32_e32 v0, v170
	s_barrier
	s_mov_b32 s14, 0xc0000
	v_lshl_add_u32 v85, s2, 9, v0
	v_cmp_gt_i32_e32 vcc, s14, v85
	s_and_saveexec_b64 s[14:15], vcc
	s_cbranch_execz .LBB0_1767
	s_load_dwordx2 s[12:13], s[12:13], 0xe8
	v_lshlrev_b32_e32 v0, 2, v0
	v_lshl_add_u32 v87, s2, 11, v0
	s_mov_b64 s[24:25], 0
	s_movk_i32 s45, 0x1000
	s_waitcnt lgkmcnt(0)
	s_add_u32 s16, s12, 0x46bc000
	s_addc_u32 s17, s13, 0
	s_add_u32 s18, s12, 0x76bc000
	s_addc_u32 s19, s13, 0
	s_add_u32 s20, s12, 0x780000
	s_addc_u32 s21, s13, 0
	s_add_u32 s22, s12, 0x2ebc000
	s_addc_u32 s23, s13, 0
	s_lshl_b32 s40, s42, 9
	s_lshl_b32 s41, s42, 11
	v_mov_b32_e32 v89, 0x800
	v_mov_b32_e32 v91, 0x100
	v_mov_b32_e32 v93, 0x7fc
	v_bfrev_b32_e32 v95, 0.5
	v_mov_b32_e32 v97, 0xfffff800
	v_mov_b32_e32 v99, 0xffffff00
	s_movk_i32 s47, 0xff
	v_mov_b32_e32 v77, 0
	s_mov_b32 s50, 0xbffff
	s_branch .LBB0_1640

.LBB0_1767:
	s_or_b64 exec, exec, s[14:15]
	s_mov_b64 s[14:15], s[0:1]
	s_getreg_b32 s16, hwreg(HW_REG_XCC_ID, 0, 4)
	s_waitcnt vmcnt(0)
	s_barrier
	s_and_saveexec_b64 s[12:13], s[38:39]
	s_cbranch_execz .LBB0_1819
	s_and_b32 s20, s16, 15
	s_load_dwordx2 s[18:19], s[0:1], 0xe8
	s_add_i32 s98, s98, 1
	s_lshl_b32 s20, s20, 8
	v_mov_b32_e32 v0, 0
	v_mov_b32_e32 v1, 1
	s_waitcnt lgkmcnt(0)
	s_add_u32 s18, s18, 0x7798000
	s_addc_u32 s19, s19, 0
	s_add_u32 s24, s18, s20
	s_addc_u32 s25, s19, 0
	s_add_u32 s26, s24, 0x1400
	s_addc_u32 s27, s25, 0
	s_add_u32 s30, s24, 0x2400
	s_addc_u32 s31, s25, 0
	global_atomic_add v0, v1, s[26:27]
	s_cmp_lg_u32 s101, 0
	s_cbranch_scc1 .Lxbn9_fol
	s_mul_i32 s21, s98, s99
	s_mov_b32 s22, 0

.Lxbn9_end:
.LBB0_1819:
	s_or_b64 exec, exec, s[12:13]
	s_mov_b64 s[20:21], s[0:1]
	s_waitcnt lgkmcnt(0)
	s_barrier
	s_load_dwordx2 s[14:15], s[20:21], 0xe8
	v_mov_b32_e32 v8, v170
	s_waitcnt lgkmcnt(0)
	s_add_u32 s18, s14, 0x46bc000
	s_addc_u32 s19, s15, 0
	s_add_u32 s16, s14, 0x2ebc000
	s_addc_u32 s17, s15, 0
	s_and_b64 vcc, exec, s[10:11]
	v_readfirstlane_b32 s45, v8
	s_cbranch_vccnz .LBB0_1835
	v_lshlrev_b32_e32 v0, 4, v8
	v_add_u32_e32 v1, 0x2000, v0
	v_ashrrev_i32_e32 v2, 31, v1
	v_lshrrev_b32_e32 v2, 22, v2
	v_add_u32_e32 v2, v1, v2
	v_ashrrev_i32_e32 v2, 10, v2
	v_mul_i32_i24_e32 v4, 0x400, v2
	v_sub_u32_e32 v1, v1, v4
	v_lshrrev_b32_e32 v4, 4, v1
	v_bitop3_b32 v1, v4, v1, 32 bitop3:0x6c
	v_ashrrev_i32_e32 v4, 31, v1
	v_lshrrev_b32_e32 v4, 26, v4
	v_add_u32_e32 v4, v1, v4
	v_lshlrev_b32_e32 v3, 5, v2
	v_ashrrev_i32_e32 v5, 6, v4
	v_and_b32_e32 v4, 0xc0, v4
	v_lshlrev_b32_e32 v2, 3, v2
	v_sub_u32_e32 v1, v1, v4
	v_mov_b32_e32 v4, 1
	v_and_b32_e32 v2, -16, v2
	v_and_b32_e32 v3, 32, v3
	v_ashrrev_i16_sdwa v1, v4, sext(v1) dst_sel:DWORD dst_unused:UNUSED_PAD src0_sel:DWORD src1_sel:BYTE_0
	v_add_u32_e32 v2, v5, v2
	v_add_u32_sdwa v1, v3, sext(v1) dst_sel:DWORD dst_unused:UNUSED_PAD src0_sel:DWORD src1_sel:WORD_0
	v_lshlrev_b32_e32 v3, 9, v2
	v_lshl_add_u32 v128, v1, 1, v3
	s_movk_i32 s12, 0x600
	s_add_u32 s47, s14, 0xe3c000
	v_mad_u64_u32 v[130:131], s[22:23], v2, s12, v[128:129]
	s_addc_u32 s72, s15, 0
	s_lshr_b32 s22, s3, 29
	v_bfe_i32 v3, v8, 27, 1
	s_add_i32 s22, s2, s22
	v_lshrrev_b32_e32 v3, 22, v3
	s_ashr_i32 s23, s22, 3
	s_and_b32 s22, s22, -8
	v_add_u32_e32 v3, v0, v3
	s_sub_i32 s22, s2, s22
	v_and_b32_e32 v3, 0xfffffc00, v3
	s_lshr_b32 s25, s22, 31
	v_sub_u32_e32 v0, v0, v3
	s_or_b32 s25, s25, 24
	v_lshrrev_b32_e32 v3, 4, v0
	s_mul_i32 s22, s25, s22
	v_ashrrev_i32_e32 v1, 31, v8
	v_bitop3_b32 v3, v3, v0, 32 bitop3:0x6c
	v_ashrrev_i32_e32 v0, 31, v0
	s_add_i32 s22, s22, s23
	v_lshrrev_b32_e32 v1, 26, v1
	v_lshrrev_b32_e32 v0, 26, v0
	s_ashr_i32 s23, s22, 31
	v_add_u32_e32 v1, v8, v1
	v_add_u32_e32 v0, v3, v0
	s_lshr_b32 s23, s23, 27
	v_ashrrev_i32_e32 v1, 6, v1
	v_ashrrev_i32_e32 v0, 6, v0
	s_add_i32 s23, s22, s23
	v_lshlrev_b32_e32 v2, 5, v1
	v_mul_i32_i24_e32 v5, 64, v0
	v_lshlrev_b32_e32 v1, 3, v1
	s_ashr_i32 s23, s23, 5
	v_sub_u32_e32 v3, v3, v5
	v_and_b32_e32 v1, -16, v1
	s_lshl_b32 s25, s23, 3
	v_and_b32_e32 v2, 32, v2
	v_ashrrev_i16_sdwa v3, v4, sext(v3) dst_sel:DWORD dst_unused:UNUSED_PAD src0_sel:DWORD src1_sel:BYTE_0
	v_add_u32_e32 v0, v0, v1
	s_sub_i32 s26, 48, s25
	s_lshl_b32 s23, s23, 5
	v_add_u32_sdwa v2, v2, sext(v3) dst_sel:DWORD dst_unused:UNUSED_PAD src0_sel:DWORD src1_sel:WORD_0
	v_lshlrev_b32_e32 v1, 9, v0
	s_min_u32 s26, s26, 8
	s_sub_i32 s27, s22, s23
	v_lshl_add_u32 v132, v2, 1, v1
	s_sext_i32_i8 s28, s27
	v_cvt_f32_ubyte0_e32 v2, s26
	v_cvt_f32_i32_e32 v1, s28
	v_rcp_iflag_f32_e32 v3, v2
	v_mad_u64_u32 v[134:135], s[22:23], v0, s12, v[132:133]
	s_ashr_i32 s24, s45, 6
	v_mul_f32_e32 v0, v1, v3
	v_trunc_f32_e32 v0, v0
	v_fma_f32 v1, -v0, v2, v1
	v_cvt_i32_f32_e32 v0, v0
	s_ashr_i32 s12, s28, 30
	s_ashr_i32 s13, s45, 8
	s_lshl_b32 s73, s24, 10
	s_or_b32 s12, s12, 1
	v_cmp_ge_f32_e64 s[22:23], |v1|, v2
	s_and_b64 s[22:23], s[22:23], exec
	s_cselect_b32 s12, s12, 0
	v_readfirstlane_b32 s22, v0
	s_add_i32 s12, s22, s12
	s_mul_i32 s22, s12, s26
	s_sub_i32 s22, s27, s22
	s_sext_i32_i8 s22, s22
	s_add_i32 s22, s25, s22
	s_ashr_i32 s23, s22, 31
	s_bfe_i64 s[28:29], s[12:13], 0x80000
	s_lshl_b64 s[26:27], s[22:23], 19
	s_lshl_b64 s[30:31], s[28:29], 9
	s_lshl_b64 s[28:29], s[28:29], 17
	s_add_u32 s54, s47, s28
	s_addc_u32 s55, s72, s29
	s_add_i32 s48, s73, 0
	s_add_i32 m0, s48, 0x10000
	v_mov_b32_e32 v133, 0
	global_load_lds_dwordx4 v132, s[54:55]
	s_add_i32 m0, s48, 0x12000
	s_add_u32 s23, s16, s26
	s_addc_u32 s25, s17, s27
	s_add_u32 s56, s23, s30
	global_load_lds_dwordx4 v128, s[54:55]
	s_addc_u32 s57, s25, s31
	s_mov_b32 m0, s48
	s_add_i32 s75, s48, 0x2000
	global_load_lds_dwordx4 v134, s[56:57]
	s_mov_b32 m0, s75
	s_add_u32 s26, s54, 0x10000
	global_load_lds_dwordx4 v130, s[56:57]
	s_addc_u32 s27, s55, 0
	s_add_i32 m0, s48, 0x14000
	v_writelane_b32 v234, s4, 2
	global_load_lds_dwordx4 v132, s[26:27]
	s_add_i32 m0, s48, 0x16000
	v_mov_b32_e32 v129, v133
	global_load_lds_dwordx4 v128, s[26:27]
	s_add_u32 s26, s56, 0x40000
	s_addc_u32 s27, s57, 0
	s_add_i32 s76, s48, 0x4000
	s_mov_b32 m0, s76
	s_add_i32 s77, s48, 0x6000
	global_load_lds_dwordx4 v134, s[26:27]
	s_mov_b32 m0, s77
	v_mov_b32_e32 v135, v133
	global_load_lds_dwordx4 v130, s[26:27]
	v_mov_b32_e32 v131, v133
	v_writelane_b32 v234, s5, 3
	s_mov_b64 s[4:5], s[38:39]
	s_mov_b32 s38, s46
	s_mov_b64 s[8:9], s[10:11]
	s_mov_b64 s[10:11], s[6:7]
	s_mov_b64 s[6:7], s[88:89]
	s_mov_b32 s46, s90
	s_mov_b32 s23, 0
	v_lshl_add_u64 v[6:7], s[54:55], 0, v[132:133]
	v_lshl_add_u64 v[4:5], s[54:55], 0, v[128:129]
	v_lshl_add_u64 v[2:3], s[56:57], 0, v[134:135]
	s_cmp_lg_u32 s13, 1
	v_lshl_add_u64 v[0:1], s[56:57], 0, v[130:131]
	s_cbranch_scc1 .LBB0_1822
	s_barrier

.Lxbn10_end:
.LBB0_1978:
	s_or_b64 exec, exec, s[12:13]
	v_readlane_b32 s8, v234, 0
	s_mov_b64 s[12:13], s[0:1]
	v_mov_b32_e32 v8, v170
	v_readlane_b32 s9, v234, 1
	s_waitcnt lgkmcnt(0)
	s_barrier
	s_and_b64 vcc, exec, s[8:9]
	v_readfirstlane_b32 s40, v8
	s_cbranch_vccnz .LBB0_1990
	v_lshlrev_b32_e32 v0, 4, v8
	v_add_u32_e32 v1, 0x2000, v0
	v_ashrrev_i32_e32 v2, 31, v1
	v_lshrrev_b32_e32 v2, 22, v2
	v_add_u32_e32 v2, v1, v2
	v_ashrrev_i32_e32 v9, 10, v2
	v_mul_i32_i24_e32 v3, 0x400, v9
	v_sub_u32_e32 v1, v1, v3
	v_lshrrev_b32_e32 v3, 4, v1
	s_load_dwordx2 s[8:9], s[12:13], 0xe8
	v_bitop3_b32 v1, v3, v1, 32 bitop3:0x6c
	v_ashrrev_i32_e32 v3, 31, v1
	v_lshrrev_b32_e32 v3, 26, v3
	v_add_u32_e32 v3, v1, v3
	v_ashrrev_i32_e32 v10, 6, v3
	v_and_b32_e32 v3, 0xc0, v3
	s_waitcnt lgkmcnt(0)
	s_add_u32 s41, s8, 0x16bc000
	v_sub_u32_e32 v1, v1, v3
	v_mov_b32_e32 v3, 1
	s_addc_u32 s45, s9, 0
	v_lshlrev_b32_e32 v2, 5, v9
	v_ashrrev_i16_sdwa v1, v3, sext(v1) dst_sel:DWORD dst_unused:UNUSED_PAD src0_sel:DWORD src1_sel:BYTE_0
	s_add_u32 s47, s8, 0x2ebc000
	v_and_b32_e32 v2, 32, v2
	v_bfe_i32 v11, v1, 0, 16
	s_addc_u32 s50, s9, 0
	v_add_u32_e32 v1, v2, v11
	v_lshlrev_b32_e32 v2, 3, v9
	s_lshr_b32 s14, s3, 29
	v_and_b32_e32 v2, 0x1ffff0, v2
	s_add_i32 s14, s2, s14
	v_add_lshl_u32 v2, v10, v2, 11
	s_ashr_i32 s15, s14, 3
	s_and_b32 s14, s14, -8
	v_lshl_add_u32 v128, v1, 1, v2
	v_bfe_i32 v2, v8, 27, 1
	s_sub_i32 s14, s2, s14
	v_lshrrev_b32_e32 v2, 22, v2
	s_lshr_b32 s16, s14, 31
	v_add_u32_e32 v2, v0, v2
	s_or_b32 s16, s16, 0x60
	v_and_b32_e32 v2, 0xfffffc00, v2
	s_mul_i32 s14, s16, s14
	v_sub_u32_e32 v0, v0, v2
	s_add_i32 s14, s14, s15
	v_lshrrev_b32_e32 v2, 4, v0
	s_ashr_i32 s15, s14, 31
	v_bitop3_b32 v2, v2, v0, 32 bitop3:0x6c
	v_ashrrev_i32_e32 v0, 31, v0
	s_lshr_b32 s15, s15, 25
	v_lshrrev_b32_e32 v0, 26, v0
	s_add_i32 s15, s14, s15
	v_ashrrev_i32_e32 v1, 31, v8
	v_add_u32_e32 v0, v2, v0
	s_ashr_i32 s15, s15, 7
	v_lshrrev_b32_e32 v1, 26, v1
	v_ashrrev_i32_e32 v13, 6, v0
	s_lshl_b32 s16, s15, 3
	v_add_u32_e32 v1, v8, v1
	v_mul_i32_i24_e32 v0, 64, v13
	s_sub_i32 s17, 48, s16
	s_lshl_b32 s15, s15, 7
	v_ashrrev_i32_e32 v12, 6, v1
	v_sub_u32_e32 v0, v2, v0
	s_min_u32 s17, s17, 8
	s_sub_i32 s18, s14, s15
	v_lshlrev_b32_e32 v1, 5, v12
	v_ashrrev_i16_sdwa v0, v3, sext(v0) dst_sel:DWORD dst_unused:UNUSED_PAD src0_sel:DWORD src1_sel:BYTE_0
	s_sext_i32_i8 s14, s18
	v_cvt_f32_ubyte0_e32 v3, s17
	v_and_b32_e32 v1, 32, v1
	v_bfe_i32 v14, v0, 0, 16
	v_cvt_f32_i32_e32 v2, s14
	v_rcp_iflag_f32_e32 v4, v3
	v_add_u32_e32 v0, v1, v14
	v_lshlrev_b32_e32 v1, 3, v12
	v_and_b32_e32 v1, 0x1ffff0, v1
	v_add_lshl_u32 v1, v13, v1, 11
	v_lshl_add_u32 v130, v0, 1, v1
	v_mul_f32_e32 v0, v2, v4
	v_trunc_f32_e32 v0, v0
	v_fma_f32 v1, -v0, v3, v2
	v_cvt_i32_f32_e32 v0, v0
	s_ashr_i32 s13, s40, 6
	s_ashr_i32 s14, s14, 30
	s_ashr_i32 s12, s40, 8
	s_lshl_b32 s51, s13, 10
	s_or_b32 s19, s14, 1
	v_cmp_ge_f32_e64 s[14:15], |v1|, v3
	s_and_b64 s[14:15], s[14:15], exec
	s_cselect_b32 s14, s19, 0
	v_readfirstlane_b32 s15, v0
	s_add_i32 s14, s15, s14
	s_mul_i32 s15, s14, s17
	s_sub_i32 s15, s18, s15
	s_sext_i32_i8 s15, s15
	s_add_i32 s28, s16, s15
	s_ashr_i32 s29, s28, 31
	s_bfe_i64 s[18:19], s[14:15], 0x80000
	s_lshl_b64 s[16:17], s[28:29], 19
	s_lshl_b64 s[18:19], s[18:19], 19
	s_add_u32 s30, s41, s18
	s_addc_u32 s31, s45, s19
	s_add_i32 s52, s51, 0
	s_add_i32 m0, s52, 0x10000
	v_mov_b32_e32 v133, 0
	global_load_lds_dwordx4 v130, s[30:31]
	s_add_i32 m0, s52, 0x12000
	s_add_u32 s34, s47, s16
	global_load_lds_dwordx4 v128, s[30:31]
	s_addc_u32 s35, s50, s17
	s_mov_b32 m0, s52
	s_add_i32 s53, s52, 0x2000
	global_load_lds_dwordx4 v130, s[34:35]
	s_mov_b32 m0, s53
	s_add_u32 s16, s30, 0x40000
	global_load_lds_dwordx4 v128, s[34:35]
	s_addc_u32 s17, s31, 0
	s_add_i32 m0, s52, 0x14000
	v_mov_b32_e32 v131, v133
	global_load_lds_dwordx4 v130, s[16:17]
	s_add_i32 m0, s52, 0x16000
	v_mov_b32_e32 v129, v133
	global_load_lds_dwordx4 v128, s[16:17]
	s_add_u32 s16, s34, 0x40000
	s_addc_u32 s17, s35, 0
	s_add_i32 s54, s52, 0x4000
	s_mov_b32 m0, s54
	s_add_i32 s55, s52, 0x6000
	global_load_lds_dwordx4 v130, s[16:17]
	s_mov_b32 m0, s55
	s_mov_b32 s56, 0
	global_load_lds_dwordx4 v128, s[16:17]
	v_lshl_add_u64 v[6:7], s[30:31], 0, v[130:131]
	v_lshl_add_u64 v[4:5], s[30:31], 0, v[128:129]
	v_lshl_add_u64 v[2:3], s[34:35], 0, v[130:131]
	s_cmp_lg_u32 s12, 1
	v_lshl_add_u64 v[0:1], s[34:35], 0, v[128:129]
	s_cbranch_scc1 .LBB0_1981
	s_barrier

.LBB0_1990:
	s_mov_b64 s[12:13], s[0:1]
	s_getreg_b32 s14, hwreg(HW_REG_XCC_ID, 0, 4)
	s_waitcnt vmcnt(0)
	s_waitcnt vmcnt(0) lgkmcnt(0)
	s_barrier
	s_and_saveexec_b64 s[8:9], s[38:39]
	s_cbranch_execz .LBB0_2042
	s_and_b32 s20, s14, 15
	s_load_dwordx2 s[18:19], s[0:1], 0xe8
	s_add_i32 s98, s98, 1
	s_lshl_b32 s20, s20, 8
	v_mov_b32_e32 v0, 0
	v_mov_b32_e32 v1, 1
	s_waitcnt lgkmcnt(0)
	s_add_u32 s18, s18, 0x7798000
	s_addc_u32 s19, s19, 0
	s_add_u32 s24, s18, s20
	s_addc_u32 s25, s19, 0
	s_add_u32 s26, s24, 0x1400
	s_addc_u32 s27, s25, 0
	s_add_u32 s30, s24, 0x2400
	s_addc_u32 s31, s25, 0
	global_atomic_add v0, v1, s[26:27]
	s_cmp_lg_u32 s101, 0
	s_cbranch_scc1 .Lxbn11_fol
	s_mul_i32 s21, s98, s99
	s_mov_b32 s22, 0

.Lxbn11_end:
.LBB0_2042:
	s_or_b64 exec, exec, s[8:9]
	s_mov_b64 s[14:15], s[0:1]
	s_waitcnt lgkmcnt(0)
	s_barrier
	s_load_dwordx2 s[16:17], s[14:15], 0xe8
	v_mov_b32_e32 v4, v170
	s_waitcnt lgkmcnt(0)
	s_add_u32 s12, s16, 0x46bc000
	s_addc_u32 s13, s17, 0
	s_and_b64 vcc, exec, s[10:11]
	v_readfirstlane_b32 s45, v4
	s_cbranch_vccnz .LBB0_2054
	v_lshlrev_b32_e32 v0, 4, v4
	v_add_u32_e32 v1, 0x2000, v0
	v_ashrrev_i32_e32 v2, 31, v1
	v_lshrrev_b32_e32 v2, 22, v2
	v_add_u32_e32 v2, v1, v2
	v_ashrrev_i32_e32 v5, 10, v2
	v_mul_i32_i24_e32 v3, 0x400, v5
	v_sub_u32_e32 v1, v1, v3
	v_lshrrev_b32_e32 v3, 4, v1
	v_bitop3_b32 v1, v3, v1, 32 bitop3:0x6c
	v_ashrrev_i32_e32 v3, 31, v1
	v_lshrrev_b32_e32 v3, 26, v3
	v_add_u32_e32 v3, v1, v3
	v_ashrrev_i32_e32 v6, 6, v3
	v_and_b32_e32 v3, 0xc0, v3
	v_sub_u32_e32 v1, v1, v3
	v_mov_b32_e32 v3, 1
	v_lshlrev_b32_e32 v2, 5, v5
	v_ashrrev_i16_sdwa v1, v3, sext(v1) dst_sel:DWORD dst_unused:UNUSED_PAD src0_sel:DWORD src1_sel:BYTE_0
	v_and_b32_e32 v2, 32, v2
	v_bfe_i32 v7, v1, 0, 16
	v_add_u32_e32 v1, v2, v7
	v_lshlrev_b32_e32 v2, 3, v5
	v_and_b32_e32 v2, -16, v2
	v_add_u32_e32 v2, v6, v2
	v_lshlrev_b32_e32 v8, 13, v2
	v_lshl_add_u32 v128, v1, 1, v8
	s_movk_i32 s8, 0xe080
	s_add_u32 s47, s16, 0x26bc000
	v_mad_u64_u32 v[130:131], s[10:11], v2, s8, v[128:129]
	v_bfe_i32 v2, v4, 27, 1
	s_addc_u32 s54, s17, 0
	v_lshrrev_b32_e32 v2, 22, v2
	s_add_u32 s55, s16, 0x779c000
	v_add_u32_e32 v2, v0, v2
	s_addc_u32 s56, s17, 0
	v_and_b32_e32 v2, 0xfffffc00, v2
	s_lshr_b32 s10, s3, 29
	v_sub_u32_e32 v0, v0, v2
	s_add_i32 s10, s2, s10
	v_lshrrev_b32_e32 v2, 4, v0
	s_ashr_i32 s11, s10, 3
	s_and_b32 s10, s10, -8
	v_bitop3_b32 v2, v2, v0, 32 bitop3:0x6c
	v_ashrrev_i32_e32 v0, 31, v0
	s_sub_i32 s10, s2, s10
	v_lshrrev_b32_e32 v0, 26, v0
	s_lshr_b32 s19, s10, 31
	v_ashrrev_i32_e32 v1, 31, v4
	v_add_u32_e32 v0, v2, v0
	s_or_b32 s19, s19, 24
	v_lshrrev_b32_e32 v1, 26, v1
	v_ashrrev_i32_e32 v9, 6, v0
	s_mul_i32 s10, s19, s10
	v_add_u32_e32 v1, v4, v1
	v_mul_i32_i24_e32 v0, 64, v9
	s_add_i32 s10, s10, s11
	v_ashrrev_i32_e32 v8, 6, v1
	v_sub_u32_e32 v0, v2, v0
	s_ashr_i32 s11, s10, 31
	v_lshlrev_b32_e32 v1, 5, v8
	v_ashrrev_i16_sdwa v0, v3, sext(v0) dst_sel:DWORD dst_unused:UNUSED_PAD src0_sel:DWORD src1_sel:BYTE_0
	s_lshr_b32 s11, s11, 27
	v_and_b32_e32 v1, 32, v1
	v_bfe_i32 v10, v0, 0, 16
	s_add_i32 s11, s10, s11
	v_add_u32_e32 v0, v1, v10
	v_lshlrev_b32_e32 v1, 3, v8
	s_ashr_i32 s11, s11, 5
	v_and_b32_e32 v1, -16, v1
	s_lshl_b32 s19, s11, 3
	v_add_u32_e32 v1, v9, v1
	s_sub_i32 s20, 48, s19
	s_lshl_b32 s11, s11, 5
	v_lshlrev_b32_e32 v2, 13, v1
	s_min_u32 s20, s20, 8
	s_sub_i32 s21, s10, s11
	v_lshl_add_u32 v132, v0, 1, v2
	s_sext_i32_i8 s22, s21
	v_cvt_f32_ubyte0_e32 v2, s20
	v_cvt_f32_i32_e32 v0, s22
	v_rcp_iflag_f32_e32 v3, v2
	v_mad_u64_u32 v[134:135], s[10:11], v1, s8, v[132:133]
	s_ashr_i32 s18, s45, 6
	v_mul_f32_e32 v1, v0, v3
	v_trunc_f32_e32 v1, v1
	v_fma_f32 v0, -v1, v2, v0
	v_cvt_i32_f32_e32 v1, v1
	s_ashr_i32 s8, s22, 30
	s_ashr_i32 s9, s45, 8
	s_lshl_b32 s57, s18, 10
	s_or_b32 s8, s8, 1
	v_cmp_ge_f32_e64 s[10:11], |v0|, v2
	s_and_b64 s[10:11], s[10:11], exec
	s_cselect_b32 s8, s8, 0
	v_readfirstlane_b32 s10, v1
	s_add_i32 s8, s10, s8
	s_mul_i32 s10, s8, s20
	s_sub_i32 s10, s21, s10
	s_sext_i32_i8 s10, s10
	s_add_i32 s10, s19, s10
	s_ashr_i32 s11, s10, 31
	s_bfe_i64 s[22:23], s[8:9], 0x80000
	s_lshl_b64 s[20:21], s[10:11], 21
	s_lshl_b64 s[22:23], s[22:23], 21
	s_add_u32 s40, s47, s22
	s_addc_u32 s41, s54, s23
	s_add_i32 s58, s57, 0
	s_add_i32 m0, s58, 0x10000
	v_mov_b32_e32 v133, 0
	global_load_lds_dwordx4 v132, s[40:41]
	s_add_i32 m0, s58, 0x12000
	s_add_u32 s48, s55, s20
	global_load_lds_dwordx4 v128, s[40:41]
	s_addc_u32 s49, s56, s21
	s_mov_b32 m0, s58
	s_add_i32 s59, s58, 0x2000
	global_load_lds_dwordx4 v134, s[48:49]
	s_mov_b32 m0, s59
	s_add_u32 s20, s40, 0x100000
	global_load_lds_dwordx4 v130, s[48:49]
	s_addc_u32 s21, s41, 0
	s_add_i32 m0, s58, 0x14000
	v_mov_b32_e32 v129, v133
	global_load_lds_dwordx4 v132, s[20:21]
	s_add_i32 m0, s58, 0x16000
	s_mov_b32 s11, 0
	global_load_lds_dwordx4 v128, s[20:21]
	s_add_u32 s20, s48, 0x4000
	s_addc_u32 s21, s49, 0
	s_add_i32 s60, s58, 0x4000
	s_mov_b32 m0, s60
	s_add_i32 s61, s58, 0x6000
	global_load_lds_dwordx4 v134, s[20:21]
	s_mov_b32 m0, s61
	v_lshl_add_u64 v[2:3], s[40:41], 0, v[132:133]
	global_load_lds_dwordx4 v130, s[20:21]
	v_lshl_add_u64 v[0:1], s[40:41], 0, v[128:129]
	v_mov_b32_e32 v135, v133
	s_cmp_lg_u32 s9, 1
	v_mov_b32_e32 v131, v133
	s_cbranch_scc1 .LBB0_2045
	s_barrier

	.amdhsa_kernel _Z4mega6Params
		.amdhsa_group_segment_fixed_size 0
		.amdhsa_private_segment_fixed_size 0
		.amdhsa_kernarg_size 512
		.amdhsa_user_sgpr_count 2
		.amdhsa_user_sgpr_dispatch_ptr 0
		.amdhsa_user_sgpr_queue_ptr 0
		.amdhsa_user_sgpr_kernarg_segment_ptr 1
		.amdhsa_user_sgpr_dispatch_id 0
		.amdhsa_user_sgpr_kernarg_preload_length 0
		.amdhsa_user_sgpr_kernarg_preload_offset 0
		.amdhsa_user_sgpr_private_segment_size 0
		.amdhsa_uses_dynamic_stack 0
		.amdhsa_enable_private_segment 0
		.amdhsa_system_sgpr_workgroup_id_x 1
		.amdhsa_system_sgpr_workgroup_id_y 0
		.amdhsa_system_sgpr_workgroup_id_z 0
		.amdhsa_system_sgpr_workgroup_info 0
		.amdhsa_system_vgpr_workitem_id 2
		.amdhsa_next_free_vgpr 235
		.amdhsa_next_free_sgpr 102
		.amdhsa_accum_offset 236
		.amdhsa_reserve_vcc 1
		.amdhsa_float_round_mode_32 0
		.amdhsa_float_round_mode_16_64 0
		.amdhsa_float_denorm_mode_32 3
		.amdhsa_float_denorm_mode_16_64 3
		.amdhsa_dx10_clamp 1
		.amdhsa_ieee_mode 1
		.amdhsa_fp16_overflow 0
		.amdhsa_tg_split 0
		.amdhsa_exception_fp_ieee_invalid_op 0
		.amdhsa_exception_fp_denorm_src 0
		.amdhsa_exception_fp_ieee_div_zero 0
		.amdhsa_exception_fp_ieee_overflow 0
		.amdhsa_exception_fp_ieee_underflow 0
		.amdhsa_exception_fp_ieee_inexact 0
		.amdhsa_exception_int_div_zero 0
	.end_amdhsa_kernel

amdhsa.kernels:
  - .agpr_count:     0
    .args:
      - .offset:         0
        .size:           256
        .value_kind:     by_value
      - .offset:         256
        .size:           4
        .value_kind:     hidden_block_count_x
      - .offset:         260
        .size:           4
        .value_kind:     hidden_block_count_y
      - .offset:         264
        .size:           4
        .value_kind:     hidden_block_count_z
      - .offset:         268
        .size:           2
        .value_kind:     hidden_group_size_x
      - .offset:         270
        .size:           2
        .value_kind:     hidden_group_size_y
      - .offset:         272
        .size:           2
        .value_kind:     hidden_group_size_z
      - .offset:         274
        .size:           2
        .value_kind:     hidden_remainder_x
      - .offset:         276
        .size:           2
        .value_kind:     hidden_remainder_y
      - .offset:         278
        .size:           2
        .value_kind:     hidden_remainder_z
      - .offset:         296
        .size:           8
        .value_kind:     hidden_global_offset_x
      - .offset:         304
        .size:           8
        .value_kind:     hidden_global_offset_y
      - .offset:         312
        .size:           8
        .value_kind:     hidden_global_offset_z
      - .offset:         320
        .size:           2
        .value_kind:     hidden_grid_dims
      - .offset:         344
        .size:           8
        .value_kind:     hidden_multigrid_sync_arg
      - .offset:         376
        .size:           4
        .value_kind:     hidden_dynamic_lds_size
    .group_segment_fixed_size: 0
    .kernarg_segment_align: 8
    .kernarg_segment_size: 512
    .language:       OpenCL C
    .language_version:
      - 2
      - 0
    .max_flat_workgroup_size: 512
    .name:           _Z4mega6Params
    .private_segment_fixed_size: 0
    .sgpr_count:     108
    .sgpr_spill_count: 4
    .symbol:         _Z4mega6Params.kd
    .uniform_work_group_size: 1
    .uses_dynamic_stack: false
    .vgpr_count:     235
    .vgpr_spill_count: 0
    .wavefront_size: 64
